# attention tile: six dead address / scalar instructions removed (left over from the pipelined QK and PV sections)
# speedup vs baseline: 1.0032x; 1.0019x over previous
; #define LAS __attribute__((address_space(3)))
; __device__ __forceinline__ void attn_phase(LAS unsigned char* lds, const bf16_t* QKVZ, const float* sinks, bf16_t* OG, int G, int bid, int tid) {
;     ...
;         for (int mt = 0; mt < 4; ++mt) {
;             const int qo0 = qh * 64 + mt * 16;
;             const size_t row = (size_t)(b * T + n * 128 + qo0 + fr);
;             const bf16_t* qp = QKVZ + row * ATT_IN + h * 64 + fq * 8;
;             const bf16x8 q0 = *(const bf16x8*)qp, q1 = *(const bf16x8*)(qp + 32);
;             const int kt0 = (qh * 4 + mt) < 6 ? (qh * 4 + mt) : 6;
;             f32x4 s[10];
; #pragma unroll
;             for (int kt = 0; kt < 10; ++kt) {
;                 const LAS unsigned char* kp = Kl + ((kt0 + kt) * 16 + fr) * KP + fq * 16;
;                 const bf16x8 k0 = *(const LAS bf16x8*)kp, k1 = *(const LAS bf16x8*)(kp + 64);
;                 f32x4 acc = (f32x4){0.f, 0.f, 0.f, 0.f};
;                 acc = __builtin_amdgcn_mfma_f32_16x16x32_bf16(k0, q0, acc, 0, 0, 0);
;                 acc = __builtin_amdgcn_mfma_f32_16x16x32_bf16(k1, q1, acc, 0, 0, 0);
;                 s[kt] = acc;
;             }
.Lmy_att_t0:
	v_add_u32_e32 v82, s1, v140
	v_mov_b64_e32 v[32:33], s[14:15]
	v_mad_i64_i32 v[84:85], s[26:27], v82, s22, v[32:33]
	v_lshl_add_u64 v[36:37], v[84:85], 0, v[72:73]
	v_mov_b64_e32 v[32:33], v[186:187]
	v_mov_b64_e32 v[34:35], v[188:189]
	v_mov_b64_e32 v[162:163], v[190:191]
	v_mov_b64_e32 v[164:165], v[192:193]
	s_mov_b32 s99, 0x14000
	s_cmp_eq_u32 s1, 48
	s_cselect_b32 s99, 0x27c4000, s99
	v_add_co_u32_e32 v194, vcc, s99, v36
	s_nop 1
	v_addc_co_u32_e32 v195, vcc, 0, v37, vcc
	global_load_dwordx4 v[186:189], v[194:195], off
	global_load_dwordx4 v[190:193], v[194:195], off offset:64
	v_lshlrev_b32_e32 v196, 1, v76
	v_mov_b32_e32 v197, v73
	v_lshl_add_u64 v[198:199], v[84:85], 0, v[196:197]
	global_load_dwordx2 v[200:201], v[198:199], off offset:3072
	global_load_dwordx2 v[202:203], v[198:199], off offset:3104
	global_load_dwordx2 v[204:205], v[198:199], off offset:3136
	global_load_dwordx2 v[206:207], v[198:199], off offset:3168
	s_min_u32 s25, s8, 6
	s_lshl_b32 s25, s25, 4
	s_add_i32 s29, s25, 32
	s_add_i32 s28, s25, 64
	s_add_i32 s27, s25, 0x60
	s_add_i32 s30, s25, 0x90
	s_or_b32 s26, s25, 0x80
	v_or_b32_e32 v248, s25, v89
	v_mad_u32_u24 v248, v248, s19, v90
	ds_read_b128 v[208:211], v248
	ds_read_b128 v[212:215], v248 offset:64
	ds_read_b128 v[216:219], v248 offset:2304
	ds_read_b128 v[220:223], v248 offset:2368
	ds_read_b128 v[224:227], v248 offset:4608
	ds_read_b128 v[228:231], v248 offset:4672
	ds_read_b128 v[232:235], v248 offset:6912
	ds_read_b128 v[236:239], v248 offset:6976
	ds_read_b128 v[240:243], v248 offset:9216
	ds_read_b128 v[244:247], v248 offset:9280
	v_subrev_u32_e32 v185, s25, v129
	v_add_u32_e32 v146, s25, v139
	v_subrev_u32_e32 v180, s25, v118
	v_subrev_u32_e32 v179, s25, v117
	v_subrev_u32_e32 v184, s25, v128
	v_subrev_u32_e32 v178, s25, v116
	v_subrev_u32_e32 v175, s25, v107
	v_subrev_u32_e32 v183, s25, v127
	v_subrev_u32_e32 v177, s25, v115
	v_subrev_u32_e32 v174, s25, v106
	v_subrev_u32_e32 v182, s25, v126
	v_subrev_u32_e32 v176, s25, v114
	v_subrev_u32_e32 v161, s25, v105
	v_subrev_u32_e32 v181, s25, v125
	v_subrev_u32_e32 v159, s25, v113
	v_subrev_u32_e32 v158, s25, v104
	v_subrev_u32_e32 v160, s25, v124
	v_subrev_u32_e32 v156, s25, v112
	v_subrev_u32_e32 v155, s25, v103
	v_subrev_u32_e32 v157, s25, v123
	v_subrev_u32_e32 v152, s25, v111
	v_subrev_u32_e32 v151, s25, v102
	v_subrev_u32_e32 v153, s25, v122
	v_subrev_u32_e32 v149, s25, v110
	v_subrev_u32_e32 v147, s25, v101
	v_subrev_u32_e32 v150, s25, v121
	v_subrev_u32_e32 v145, s25, v109
	v_subrev_u32_e32 v144, s25, v100
	v_subrev_u32_e32 v148, s25, v120
	v_subrev_u32_e32 v143, s25, v108
	v_subrev_u32_e32 v142, s25, v98
	v_ashrrev_i32_e32 v83, 31, v82
	v_add_u32_e32 v139, -16, v139
	s_waitcnt lgkmcnt(8)
	v_mfma_f32_16x16x32_bf16 v[68:71], v[208:211], v[32:35], 0
	v_mfma_f32_16x16x32_bf16 v[68:71], v[212:215], v[162:165], v[68:71]
	s_waitcnt lgkmcnt(6)
	v_mfma_f32_16x16x32_bf16 v[64:67], v[216:219], v[32:35], 0
	v_mfma_f32_16x16x32_bf16 v[64:67], v[220:223], v[162:165], v[64:67]
	ds_read_b128 v[208:211], v248 offset:11520
	ds_read_b128 v[212:215], v248 offset:11584
	s_waitcnt lgkmcnt(6)
	v_mfma_f32_16x16x32_bf16 v[60:63], v[224:227], v[32:35], 0
	v_mfma_f32_16x16x32_bf16 v[60:63], v[228:231], v[162:165], v[60:63]
	ds_read_b128 v[216:219], v248 offset:13824
	ds_read_b128 v[220:223], v248 offset:13888
	s_waitcnt lgkmcnt(6)
	v_mfma_f32_16x16x32_bf16 v[56:59], v[232:235], v[32:35], 0
	v_mfma_f32_16x16x32_bf16 v[56:59], v[236:239], v[162:165], v[56:59]
	ds_read_b128 v[224:227], v248 offset:16128
	ds_read_b128 v[228:231], v248 offset:16192
	s_waitcnt lgkmcnt(6)
	v_mfma_f32_16x16x32_bf16 v[52:55], v[240:243], v[32:35], 0
	v_mfma_f32_16x16x32_bf16 v[52:55], v[244:247], v[162:165], v[52:55]
	ds_read_b128 v[232:235], v248 offset:18432
	ds_read_b128 v[236:239], v248 offset:18496
	s_waitcnt lgkmcnt(6)
	v_mfma_f32_16x16x32_bf16 v[48:51], v[208:211], v[32:35], 0
	v_mfma_f32_16x16x32_bf16 v[48:51], v[212:215], v[162:165], v[48:51]
	ds_read_b128 v[240:243], v248 offset:20736
	ds_read_b128 v[244:247], v248 offset:20800
	s_waitcnt lgkmcnt(6)
	v_mfma_f32_16x16x32_bf16 v[44:47], v[216:219], v[32:35], 0
	v_mfma_f32_16x16x32_bf16 v[44:47], v[220:223], v[162:165], v[44:47]
	s_waitcnt lgkmcnt(4)
	v_mfma_f32_16x16x32_bf16 v[40:43], v[224:227], v[32:35], 0
	v_mfma_f32_16x16x32_bf16 v[40:43], v[228:231], v[162:165], v[40:43]
	s_waitcnt lgkmcnt(2)
	v_mfma_f32_16x16x32_bf16 v[36:39], v[232:235], v[32:35], 0
	v_mfma_f32_16x16x32_bf16 v[36:39], v[236:239], v[162:165], v[36:39]
	s_waitcnt lgkmcnt(0)
; __device__ __forceinline__ void attn_phase(LAS unsigned char* lds, const bf16_t* QKVZ, const float* sinks, bf16_t* OG, int G, int bid, int tid) {
;     ...
;             const int qi = 128 + qo0 + fr;
;             float mx = sink2;
; #pragma unroll
;             for (int kt = 0; kt < 10; ++kt)
; #pragma unroll
;                 for (int r = 0; r < 4; ++r) { const int si = (kt0 + kt) * 16 + 4 * fq + r, df = qi - si; const bool ok = (df >= 0) && (df < 128) && (n > 0 || si >= 128);
;                     const float v = ok ? s[kt][r] : -1e30f; s[kt][r] = v; mx = fmaxf(mx, v); }
;             mx = fmaxf(mx, __shfl_xor(mx, 16)); mx = fmaxf(mx, __shfl_xor(mx, 32));
	v_mfma_f32_16x16x32_bf16 v[32:35], v[240:243], v[32:35], 0
	v_mfma_f32_16x16x32_bf16 v[32:35], v[244:247], v[162:165], v[32:35]
	v_or_b32_e32 v154, s25, v76
	v_add_u32_e32 v162, s1, v99
	v_add_u32_e32 v163, v162, v185
	v_cmp_gt_u32_e32 vcc, s20, v163
	s_and_b64 vcc, s[12:13], vcc
	v_add_u32_e32 v163, 0xffffff80, v146
	v_cndmask_b32_e32 v68, v138, v68, vcc
	v_cmp_lt_u32_e32 vcc, s23, v163
	s_and_b64 vcc, s[12:13], vcc
	v_add_u32_e32 v164, v162, v180
	v_cndmask_b32_e32 v69, v138, v69, vcc
	v_cmp_gt_u32_e32 vcc, s20, v164
	s_and_b64 vcc, s[12:13], vcc
	v_add_u32_e32 v164, v162, v179
	v_cndmask_b32_e32 v70, v138, v70, vcc
	v_cmp_gt_u32_e32 vcc, s20, v164
	s_and_b64 vcc, s[12:13], vcc
	v_add_u32_e32 v164, v162, v184
	v_cndmask_b32_e32 v71, v138, v71, vcc
	v_cmp_gt_u32_e32 vcc, s20, v164
	s_and_b64 vcc, s[12:13], vcc
	v_add_u32_e32 v164, 0xffffff90, v146
	v_cndmask_b32_e32 v64, v138, v64, vcc
	v_cmp_lt_u32_e32 vcc, s23, v164
	s_and_b64 vcc, s[12:13], vcc
	v_add_u32_e32 v164, v162, v178
	v_cndmask_b32_e32 v65, v138, v65, vcc
	v_cmp_gt_u32_e32 vcc, s20, v164
	s_and_b64 vcc, s[12:13], vcc
	v_add_u32_e32 v164, v162, v175
	v_cndmask_b32_e32 v66, v138, v66, vcc
	v_cmp_gt_u32_e32 vcc, s20, v164
	s_and_b64 vcc, s[12:13], vcc
	s_cmp_gt_u32 s8, 5
	v_add_u32_e32 v165, v162, v183
	s_cselect_b64 s[30:31], -1, 0
	v_cndmask_b32_e32 v67, v138, v67, vcc
	v_cmp_gt_u32_e32 vcc, s20, v165
	s_or_b64 s[30:31], s[12:13], s[30:31]
	s_and_b64 vcc, vcc, s[30:31]
	v_add_u32_e32 v165, 0xffffffa0, v146
	v_cndmask_b32_e32 v60, v138, v60, vcc
	v_cmp_lt_u32_e32 vcc, s23, v165
	s_and_b64 vcc, vcc, s[30:31]
	v_add_u32_e32 v165, v162, v177
	v_cndmask_b32_e32 v61, v138, v61, vcc
	v_cmp_gt_u32_e32 vcc, s20, v165
	s_and_b64 vcc, vcc, s[30:31]
	v_add_u32_e32 v165, v162, v174
	v_cndmask_b32_e32 v62, v138, v62, vcc
	v_cmp_gt_u32_e32 vcc, s20, v165
	s_and_b64 vcc, vcc, s[30:31]
	s_cmp_gt_u32 s8, 4
	v_add_u32_e32 v165, v162, v182
	s_cselect_b64 s[30:31], -1, 0
	v_cndmask_b32_e32 v63, v138, v63, vcc
	v_cmp_gt_u32_e32 vcc, s20, v165
	s_or_b64 s[30:31], s[12:13], s[30:31]
	s_and_b64 vcc, vcc, s[30:31]
	v_add_u32_e32 v165, 0xffffffb0, v146
	v_cndmask_b32_e32 v56, v138, v56, vcc
	v_cmp_lt_u32_e32 vcc, s23, v165
	s_and_b64 vcc, vcc, s[30:31]
	v_add_u32_e32 v165, v162, v176
	v_cndmask_b32_e32 v57, v138, v57, vcc
	v_cmp_gt_u32_e32 vcc, s20, v165
	s_and_b64 vcc, vcc, s[30:31]
	v_add_u32_e32 v161, v162, v161
	v_cndmask_b32_e32 v58, v138, v58, vcc
	v_cmp_gt_u32_e32 vcc, s20, v161
	s_and_b64 vcc, vcc, s[30:31]
	s_cmp_gt_u32 s8, 3
	v_add_u32_e32 v165, v162, v181
	s_cselect_b64 s[30:31], -1, 0
	v_cndmask_b32_e32 v59, v138, v59, vcc
	v_cmp_gt_u32_e32 vcc, s20, v165
	s_or_b64 s[30:31], s[12:13], s[30:31]
	s_and_b64 vcc, vcc, s[30:31]
	v_subrev_u32_e32 v165, 64, v146
	v_cndmask_b32_e32 v52, v138, v52, vcc
	v_cmp_lt_u32_e32 vcc, s23, v165
	s_and_b64 vcc, vcc, s[30:31]
	v_add_u32_e32 v159, v162, v159
	v_cndmask_b32_e32 v53, v138, v53, vcc
	v_cmp_gt_u32_e32 vcc, s20, v159
	s_and_b64 vcc, vcc, s[30:31]
	v_add_u32_e32 v158, v162, v158
	v_cndmask_b32_e32 v54, v138, v54, vcc
	v_cmp_gt_u32_e32 vcc, s20, v158
	s_and_b64 vcc, vcc, s[30:31]
	s_cmp_gt_u32 s8, 2
	v_add_u32_e32 v159, v162, v160
	s_cselect_b64 s[30:31], -1, 0
	v_cndmask_b32_e32 v55, v138, v55, vcc
	v_cmp_gt_u32_e32 vcc, s20, v159
	s_or_b64 s[30:31], s[12:13], s[30:31]
	s_and_b64 vcc, vcc, s[30:31]
	v_subrev_u32_e32 v159, 48, v146
	v_cndmask_b32_e32 v48, v138, v48, vcc
	v_cmp_lt_u32_e32 vcc, s23, v159
	s_and_b64 vcc, vcc, s[30:31]
	v_add_u32_e32 v156, v162, v156
	v_cndmask_b32_e32 v49, v138, v49, vcc
	v_cmp_gt_u32_e32 vcc, s20, v156
	s_and_b64 vcc, vcc, s[30:31]
	v_add_u32_e32 v155, v162, v155
	v_cndmask_b32_e32 v50, v138, v50, vcc
	v_cmp_gt_u32_e32 vcc, s20, v155
	s_and_b64 vcc, vcc, s[30:31]
	s_cmp_gt_u32 s8, 1
	v_add_u32_e32 v157, v162, v157
	s_cselect_b64 s[30:31], -1, 0
	v_cndmask_b32_e32 v51, v138, v51, vcc
	v_cmp_gt_u32_e32 vcc, s20, v157
	s_or_b64 s[30:31], s[12:13], s[30:31]
	s_and_b64 vcc, vcc, s[30:31]
	v_subrev_u32_e32 v157, 32, v146
	v_cndmask_b32_e32 v44, v138, v44, vcc
	v_cmp_lt_u32_e32 vcc, s23, v157
	s_and_b64 vcc, vcc, s[30:31]
	v_add_u32_e32 v152, v162, v152
	v_cndmask_b32_e32 v45, v138, v45, vcc
	v_cmp_gt_u32_e32 vcc, s20, v152
	s_and_b64 vcc, vcc, s[30:31]
	v_add_u32_e32 v151, v162, v151
	v_cndmask_b32_e32 v46, v138, v46, vcc
	v_cmp_gt_u32_e32 vcc, s20, v151
	v_max3_f32 v163, v141, v68, v69
	s_and_b64 vcc, vcc, s[30:31]
	s_or_b32 s30, s8, s0
	v_max3_f32 v163, v163, v70, v71
	v_add_u32_e32 v152, v162, v153
	s_cmp_lg_u32 s30, 0
	v_max3_f32 v163, v163, v64, v65
	v_cndmask_b32_e32 v47, v138, v47, vcc
	v_cmp_gt_u32_e32 vcc, s20, v152
	s_cselect_b64 s[30:31], -1, 0
	v_max3_f32 v163, v163, v66, v67
	s_and_b64 vcc, s[30:31], vcc
	v_add_u32_e32 v152, -16, v146
	v_max3_f32 v163, v163, v60, v61
	v_cndmask_b32_e32 v40, v138, v40, vcc
	v_cmp_lt_u32_e32 vcc, s23, v152
	v_max3_f32 v163, v163, v62, v63
	s_and_b64 vcc, s[30:31], vcc
	v_add_u32_e32 v149, v162, v149
	v_max3_f32 v163, v163, v56, v57
	v_cndmask_b32_e32 v41, v138, v41, vcc
	v_cmp_gt_u32_e32 vcc, s20, v149
	v_max3_f32 v161, v163, v58, v59
	s_and_b64 vcc, s[30:31], vcc
	v_add_u32_e32 v147, v162, v147
	v_max3_f32 v161, v161, v52, v53
	v_cndmask_b32_e32 v42, v138, v42, vcc
	v_cmp_gt_u32_e32 vcc, s20, v147
	v_max3_f32 v158, v161, v54, v55
	s_and_b64 vcc, s[30:31], vcc
	v_add_u32_e32 v150, v162, v150
	v_max3_f32 v158, v158, v48, v49
	v_cndmask_b32_e32 v43, v138, v43, vcc
	v_cmp_gt_u32_e32 vcc, s20, v150
	v_max3_f32 v155, v158, v50, v51
	v_add_u32_e32 v145, v162, v145
	v_cndmask_b32_e32 v36, v138, v36, vcc
	v_cmp_lt_u32_e32 vcc, s23, v146
	v_max3_f32 v155, v155, v44, v45
	v_add_u32_e32 v144, v162, v144
	v_cndmask_b32_e32 v37, v138, v37, vcc
	v_cmp_gt_u32_e32 vcc, s20, v145
	v_max3_f32 v151, v155, v46, v47
	v_add_u32_e32 v145, v162, v148
	v_cndmask_b32_e32 v38, v138, v38, vcc
	v_cmp_gt_u32_e32 vcc, s20, v144
	v_max3_f32 v151, v151, v40, v41
	v_max3_f32 v147, v151, v42, v43
	v_cndmask_b32_e32 v39, v138, v39, vcc
	v_cmp_gt_u32_e32 vcc, s20, v145
	v_add_u32_e32 v145, 16, v146
	v_add_u32_e32 v143, v162, v143
	v_cndmask_b32_e32 v32, v138, v32, vcc
	v_cmp_lt_u32_e32 vcc, s23, v145
	v_max3_f32 v147, v147, v36, v37
	v_add_u32_e32 v142, v162, v142
	v_cndmask_b32_e32 v33, v138, v33, vcc
	v_cmp_gt_u32_e32 vcc, s20, v143
	v_max3_f32 v144, v147, v38, v39
	v_max3_f32 v144, v144, v32, v33
	v_cndmask_b32_e32 v34, v138, v34, vcc
	v_cmp_gt_u32_e32 vcc, s20, v142
	v_or_b32_e32 v164, s29, v76
	v_or_b32_e32 v163, s28, v76
	v_cndmask_b32_e32 v35, v138, v35, vcc
	v_max3_f32 v142, v144, v34, v35
	v_mov_b32_e32 v143, v142
	s_nop 1
	v_permlane16_swap_b32_e32 v142, v143
	v_or_b32_e32 v156, s27, v76
	v_or_b32_e32 v149, s26, v76
	s_add_i32 s1, s1, 16
	s_add_i32 s8, s8, 1
	s_waitcnt lgkmcnt(0)
; __device__ __forceinline__ u32x4 pack8(const f32x4 a, const f32x4 b) { u32x4 w; w.x = cvt_pk_bf16(a[0], a[1]); w.y = cvt_pk_bf16(a[2], a[3]); w.z = cvt_pk_bf16(b[0], b[1]); w.w = cvt_pk_bf16(b[2], b[3]); return w; }
; #define LAS __attribute__((address_space(3)))
; __device__ __forceinline__ void attn_phase(LAS unsigned char* lds, const bf16_t* QKVZ, const float* sinks, bf16_t* OG, int G, int bid, int tid) {
;     ...
;             mx = fmaxf(mx, __shfl_xor(mx, 16)); mx = fmaxf(mx, __shfl_xor(mx, 32));
;             float sum = 0.f;
; #pragma unroll
;             for (int kt = 0; kt < 10; ++kt)
; #pragma unroll
;                 for (int r = 0; r < 4; ++r) { const float p = __builtin_amdgcn_exp2f(s[kt][r] - mx); s[kt][r] = p; sum += p; }
;             sum += __shfl_xor(sum, 16); sum += __shfl_xor(sum, 32);
;             sum += __builtin_amdgcn_exp2f(sink2 - mx);
;             const float inv = 1.0f / sum;
;             f32x4 o[4];
; #pragma unroll
;             for (int dt = 0; dt < 4; ++dt) o[dt] = (f32x4){0.f, 0.f, 0.f, 0.f};
; #pragma unroll
;             for (int kk = 0; kk < 5; ++kk) {
;                 const u32x4 pw = pack8(s[2 * kk], s[2 * kk + 1]);
;                 const bf16x8 pf = __builtin_bit_cast(bf16x8, pw);
; #pragma unroll
;                 for (int dt = 0; dt < 4; ++dt) {
;                     const int d = dt * 16 + fr, sw = ((d >> 3) & 7) << 2, keyA = 16 * (kt0 + 2 * kk) + 4 * fq, keyB = keyA + 16;
;                     const u32x2 va = *(const LAS u32x2*)(Vt + d * VP + ((keyA ^ sw) * 2)), vb = *(const LAS u32x2*)(Vt + d * VP + ((keyB ^ sw) * 2));
	v_max_f32_e32 v143, v143, v143
	v_max_f32_e32 v142, v142, v143
	v_mov_b32_e32 v143, v142
	s_nop 1
	v_permlane32_swap_b32_e32 v142, v143
	s_cmp_eq_u32 s1, 64
	s_waitcnt lgkmcnt(0)
	v_max_f32_e32 v143, v143, v143
	v_max_f32_e32 v142, v142, v143
	v_sub_f32_e32 v68, v68, v142
	v_exp_f32_e32 v68, v68
	v_sub_f32_e32 v69, v69, v142
	v_exp_f32_e32 v69, v69
	v_sub_f32_e32 v70, v70, v142
	v_exp_f32_e32 v70, v70
	v_sub_f32_e32 v71, v71, v142
	v_exp_f32_e32 v71, v71
	v_sub_f32_e32 v64, v64, v142
	v_add_f32_e32 v143, 0, v68
	v_exp_f32_e32 v64, v64
	v_sub_f32_e32 v65, v65, v142
	v_add_f32_e32 v143, v69, v143
	v_exp_f32_e32 v65, v65
	v_sub_f32_e32 v66, v66, v142
	v_add_f32_e32 v143, v70, v143
	v_exp_f32_e32 v66, v66
	v_sub_f32_e32 v67, v67, v142
	v_add_f32_e32 v143, v71, v143
	v_exp_f32_e32 v67, v67
	v_sub_f32_e32 v60, v60, v142
	v_add_f32_e32 v143, v64, v143
	v_exp_f32_e32 v60, v60
	v_sub_f32_e32 v61, v61, v142
	v_add_f32_e32 v143, v65, v143
	v_exp_f32_e32 v61, v61
	v_sub_f32_e32 v62, v62, v142
	v_add_f32_e32 v143, v66, v143
	v_exp_f32_e32 v62, v62
	v_sub_f32_e32 v63, v63, v142
	v_add_f32_e32 v143, v67, v143
	v_exp_f32_e32 v63, v63
	v_sub_f32_e32 v56, v56, v142
	v_add_f32_e32 v143, v60, v143
	v_exp_f32_e32 v56, v56
	v_sub_f32_e32 v57, v57, v142
	v_add_f32_e32 v143, v61, v143
	v_exp_f32_e32 v57, v57
	v_sub_f32_e32 v58, v58, v142
	v_add_f32_e32 v143, v62, v143
	v_exp_f32_e32 v58, v58
	v_sub_f32_e32 v59, v59, v142
	v_add_f32_e32 v143, v63, v143
	v_exp_f32_e32 v59, v59
	v_sub_f32_e32 v52, v52, v142
	v_add_f32_e32 v143, v56, v143
	v_exp_f32_e32 v144, v52
	v_add_f32_e32 v143, v57, v143
	v_add_f32_e32 v143, v58, v143
	v_add_f32_e32 v143, v59, v143
	v_sub_f32_e32 v53, v53, v142
	v_add_f32_e32 v52, v144, v143
	v_exp_f32_e32 v143, v53
	v_sub_f32_e32 v53, v54, v142
	v_exp_f32_e32 v145, v53
	v_sub_f32_e32 v53, v55, v142
	v_exp_f32_e32 v146, v53
	v_sub_f32_e32 v48, v48, v142
	v_exp_f32_e32 v147, v48
	v_sub_f32_e32 v49, v49, v142
	v_add_f32_e32 v52, v143, v52
	v_exp_f32_e32 v148, v49
	v_sub_f32_e32 v49, v50, v142
	v_add_f32_e32 v52, v145, v52
	v_exp_f32_e32 v150, v49
	v_sub_f32_e32 v49, v51, v142
	v_add_f32_e32 v52, v146, v52
	v_exp_f32_e32 v151, v49
	v_sub_f32_e32 v44, v44, v142
	v_add_f32_e32 v48, v147, v52
	v_exp_f32_e32 v152, v44
	v_sub_f32_e32 v45, v45, v142
	v_add_f32_e32 v48, v148, v48
	v_exp_f32_e32 v153, v45
	v_sub_f32_e32 v45, v46, v142
	v_add_f32_e32 v48, v150, v48
	v_exp_f32_e32 v155, v45
	v_sub_f32_e32 v45, v47, v142
	v_add_f32_e32 v48, v151, v48
	v_exp_f32_e32 v157, v45
	v_sub_f32_e32 v40, v40, v142
	v_add_f32_e32 v44, v152, v48
	v_exp_f32_e32 v158, v40
	v_sub_f32_e32 v41, v41, v142
	v_add_f32_e32 v44, v153, v44
	v_exp_f32_e32 v159, v41
	v_sub_f32_e32 v41, v42, v142
	v_add_f32_e32 v44, v155, v44
	v_exp_f32_e32 v160, v41
	v_sub_f32_e32 v41, v43, v142
	v_add_f32_e32 v44, v157, v44
	v_exp_f32_e32 v161, v41
	v_sub_f32_e32 v36, v36, v142
	v_add_f32_e32 v40, v158, v44
	v_exp_f32_e32 v162, v36
	v_sub_f32_e32 v37, v37, v142
	v_add_f32_e32 v40, v159, v40
	v_exp_f32_e32 v165, v37
	v_sub_f32_e32 v37, v38, v142
	v_add_f32_e32 v40, v160, v40
	v_exp_f32_e32 v166, v37
	v_sub_f32_e32 v37, v39, v142
	v_add_f32_e32 v40, v161, v40
	v_exp_f32_e32 v167, v37
	v_sub_f32_e32 v32, v32, v142
	v_add_f32_e32 v36, v162, v40
	v_exp_f32_e32 v168, v32
	v_sub_f32_e32 v33, v33, v142
	v_add_f32_e32 v36, v165, v36
	v_exp_f32_e32 v169, v33
	v_sub_f32_e32 v33, v34, v142
	v_add_f32_e32 v36, v166, v36
	v_exp_f32_e32 v170, v33
	v_sub_f32_e32 v33, v35, v142
	v_add_f32_e32 v36, v167, v36
	v_exp_f32_e32 v171, v33
	v_add_f32_e32 v32, v168, v36
	v_add_f32_e32 v32, v169, v32
	v_add_f32_e32 v32, v170, v32
	v_add_f32_e32 v32, v171, v32
	v_mov_b32_e32 v33, v32
	s_nop 1
	v_permlane16_swap_b32_e32 v32, v33
	v_add_u32_e32 v50, 16, v154
	v_bitop3_b32 v36, s25, v93, v76 bitop3:0x36
	v_xor_b32_e32 v38, v50, v93
	v_bitop3_b32 v40, s25, v95, v76 bitop3:0x36
	s_waitcnt lgkmcnt(0)
	v_add_f32_e32 v32, v32, v33
	v_mov_b32_e32 v33, v32
	s_nop 1
	v_permlane32_swap_b32_e32 v32, v33
	v_xor_b32_e32 v42, v50, v95
	v_bitop3_b32 v44, s25, v96, v76 bitop3:0x36
	v_xor_b32_e32 v46, v50, v96
	v_bitop3_b32 v48, s25, v97, v76 bitop3:0x36
	s_waitcnt lgkmcnt(0)
	v_add_f32_e32 v32, v32, v33
	v_sub_f32_e32 v33, v141, v142
	v_exp_f32_e32 v33, v33
	v_xor_b32_e32 v50, v50, v97
	v_lshl_add_u32 v36, v36, 1, v94
	v_lshl_add_u32 v38, v38, 1, v94
	v_lshl_add_u32 v40, v40, 1, v94
	v_lshl_add_u32 v42, v42, 1, v94
	v_lshl_add_u32 v44, v44, 1, v94
	v_lshl_add_u32 v46, v46, 1, v94
	v_lshl_add_u32 v48, v48, 1, v94
	v_lshl_add_u32 v50, v50, 1, v94
	v_mov_b32_e32 v208, v36
	v_mov_b32_e32 v209, v38
	v_mov_b32_e32 v210, v40
	v_mov_b32_e32 v211, v42
	v_mov_b32_e32 v212, v44
	v_mov_b32_e32 v213, v46
	v_mov_b32_e32 v214, v48
	v_mov_b32_e32 v215, v50
	v_add_f32_e32 v142, v33, v32
	v_cvt_pk_bf16_f32 v32, v68, v69
	v_cvt_pk_bf16_f32 v33, v70, v71
	v_cvt_pk_bf16_f32 v34, v64, v65
	v_cvt_pk_bf16_f32 v35, v66, v67
	ds_read_b64 v[36:37], v36 offset:36864
	ds_read_b64 v[38:39], v38 offset:36864
	ds_read_b64 v[40:41], v40 offset:45312
	ds_read_b64 v[42:43], v42 offset:45312
	ds_read_b64 v[44:45], v44 offset:53760
	ds_read_b64 v[46:47], v46 offset:53760
	ds_read_b64 v[48:49], v48 offset:62208
	ds_read_b64 v[50:51], v50 offset:62208
	ds_read_b64 v[232:233], v208 offset:36928
	ds_read_b64 v[234:235], v209 offset:36928
	ds_read_b64 v[236:237], v210 offset:45376
	ds_read_b64 v[238:239], v211 offset:45376
	ds_read_b64 v[240:241], v212 offset:53824
	ds_read_b64 v[242:243], v213 offset:53824
	ds_read_b64 v[244:245], v214 offset:62272
	ds_read_b64 v[246:247], v215 offset:62272
	s_waitcnt lgkmcnt(14)
	v_mfma_f32_16x16x32_bf16 v[36:39], v[36:39], v[32:35], 0
	s_waitcnt lgkmcnt(12)
; __device__ __forceinline__ u32x4 pack8(const f32x4 a, const f32x4 b) { u32x4 w; w.x = cvt_pk_bf16(a[0], a[1]); w.y = cvt_pk_bf16(a[2], a[3]); w.z = cvt_pk_bf16(b[0], b[1]); w.w = cvt_pk_bf16(b[2], b[3]); return w; }
; #define LAS __attribute__((address_space(3)))
; __device__ __forceinline__ void attn_phase(LAS unsigned char* lds, const bf16_t* QKVZ, const float* sinks, bf16_t* OG, int G, int bid, int tid) {
;     ...
;             const float inv = 1.0f / sum;
;             f32x4 o[4];
; #pragma unroll
;             for (int dt = 0; dt < 4; ++dt) o[dt] = (f32x4){0.f, 0.f, 0.f, 0.f};
; #pragma unroll
;             for (int kk = 0; kk < 5; ++kk) {
;                 const u32x4 pw = pack8(s[2 * kk], s[2 * kk + 1]);
;                 const bf16x8 pf = __builtin_bit_cast(bf16x8, pw);
; #pragma unroll
;                 for (int dt = 0; dt < 4; ++dt) {
;                     const int d = dt * 16 + fr, sw = ((d >> 3) & 7) << 2, keyA = 16 * (kt0 + 2 * kk) + 4 * fq, keyB = keyA + 16;
;                     const u32x2 va = *(const LAS u32x2*)(Vt + d * VP + ((keyA ^ sw) * 2)), vb = *(const LAS u32x2*)(Vt + d * VP + ((keyB ^ sw) * 2));
;                     const u32x4 vw = (u32x4){va.x, va.y, vb.x, vb.y};
;                     o[dt] = __builtin_amdgcn_mfma_f32_16x16x32_bf16(__builtin_bit_cast(bf16x8, vw), pf, o[dt], 0, 0, 0);
;                 }
;             }
	v_mfma_f32_16x16x32_bf16 v[40:43], v[40:43], v[32:35], 0
	s_waitcnt lgkmcnt(10)
	v_mfma_f32_16x16x32_bf16 v[44:47], v[44:47], v[32:35], 0
	s_waitcnt lgkmcnt(8)
	v_mfma_f32_16x16x32_bf16 v[32:35], v[48:51], v[32:35], 0
	v_cvt_pk_bf16_f32 v48, v60, v61
	v_cvt_pk_bf16_f32 v49, v62, v63
	v_cvt_pk_bf16_f32 v50, v56, v57
	v_cvt_pk_bf16_f32 v51, v58, v59
	s_nop 1
	ds_read_b64 v[216:217], v208 offset:36992
	ds_read_b64 v[218:219], v209 offset:36992
	ds_read_b64 v[220:221], v210 offset:45440
	ds_read_b64 v[222:223], v211 offset:45440
	ds_read_b64 v[224:225], v212 offset:53888
	ds_read_b64 v[226:227], v213 offset:53888
	ds_read_b64 v[228:229], v214 offset:62336
	ds_read_b64 v[230:231], v215 offset:62336
	s_waitcnt lgkmcnt(8)
	v_mfma_f32_16x16x32_bf16 v[36:39], v[232:235], v[48:51], v[36:39]
	v_mfma_f32_16x16x32_bf16 v[40:43], v[236:239], v[48:51], v[40:43]
	v_mfma_f32_16x16x32_bf16 v[44:47], v[240:243], v[48:51], v[44:47]
	v_mfma_f32_16x16x32_bf16 v[32:35], v[244:247], v[48:51], v[32:35]
	v_cvt_pk_bf16_f32 v248, v144, v143
	v_cvt_pk_bf16_f32 v249, v145, v146
	v_cvt_pk_bf16_f32 v250, v147, v148
	v_cvt_pk_bf16_f32 v251, v150, v151
	s_nop 1
	ds_read_b64 v[232:233], v208 offset:37056
	ds_read_b64 v[234:235], v209 offset:37056
	ds_read_b64 v[236:237], v210 offset:45504
	ds_read_b64 v[238:239], v211 offset:45504
	ds_read_b64 v[240:241], v212 offset:53952
	ds_read_b64 v[242:243], v213 offset:53952
	ds_read_b64 v[244:245], v214 offset:62400
	ds_read_b64 v[246:247], v215 offset:62400
	s_waitcnt lgkmcnt(8)
	v_mfma_f32_16x16x32_bf16 v[36:39], v[216:219], v[248:251], v[36:39]
	v_mfma_f32_16x16x32_bf16 v[40:43], v[220:223], v[248:251], v[40:43]
	v_mfma_f32_16x16x32_bf16 v[44:47], v[224:227], v[248:251], v[44:47]
	v_mfma_f32_16x16x32_bf16 v[32:35], v[228:231], v[248:251], v[32:35]
	v_cvt_pk_bf16_f32 v48, v152, v153
	v_cvt_pk_bf16_f32 v49, v155, v157
	v_cvt_pk_bf16_f32 v50, v158, v159
	v_cvt_pk_bf16_f32 v51, v160, v161
	s_nop 1
	ds_read_b64 v[216:217], v208 offset:37120
	ds_read_b64 v[218:219], v209 offset:37120
	ds_read_b64 v[220:221], v210 offset:45568
	ds_read_b64 v[222:223], v211 offset:45568
	ds_read_b64 v[224:225], v212 offset:54016
	ds_read_b64 v[226:227], v213 offset:54016
	ds_read_b64 v[228:229], v214 offset:62464
	ds_read_b64 v[230:231], v215 offset:62464
	s_waitcnt lgkmcnt(8)
	v_mfma_f32_16x16x32_bf16 v[36:39], v[232:235], v[48:51], v[36:39]
	v_mfma_f32_16x16x32_bf16 v[40:43], v[236:239], v[48:51], v[40:43]
	v_mfma_f32_16x16x32_bf16 v[52:55], v[240:243], v[48:51], v[44:47]
	v_mfma_f32_16x16x32_bf16 v[32:35], v[244:247], v[48:51], v[32:35]
	v_cvt_pk_bf16_f32 v248, v162, v165
	v_cvt_pk_bf16_f32 v249, v166, v167
	v_cvt_pk_bf16_f32 v250, v168, v169
	v_cvt_pk_bf16_f32 v251, v170, v171
	s_nop 1
	s_waitcnt lgkmcnt(0)
	v_mfma_f32_16x16x32_bf16 v[44:47], v[216:219], v[248:251], v[36:39]
	v_mfma_f32_16x16x32_bf16 v[40:43], v[220:223], v[248:251], v[40:43]
	v_mfma_f32_16x16x32_bf16 v[36:39], v[224:227], v[248:251], v[52:55]
	v_mfma_f32_16x16x32_bf16 v[32:35], v[228:231], v[248:251], v[32:35]
	v_div_scale_f32 v48, s[26:27], v142, v142, 1.0
	v_rcp_f32_e32 v49, v48
	s_nop 0
	v_fma_f32 v50, -v48, v49, 1.0
	v_fmac_f32_e32 v49, v50, v49
	v_div_scale_f32 v50, vcc, 1.0, v142, 1.0
	v_mul_f32_e32 v51, v50, v49
	v_fma_f32 v52, -v48, v51, v50
	v_fmac_f32_e32 v51, v52, v49
	v_fma_f32 v48, -v48, v51, v50
	v_div_fmas_f32 v48, v48, v49, v51
	v_div_fixup_f32 v52, v48, v142, 1.0
	v_lshlrev_b32_e32 v48, 1, v76
	v_mov_b32_e32 v49, v73
	v_lshl_add_u64 v[50:51], v[84:85], 0, v[48:49]
	v_mul_f32_e32 v44, v52, v44
	v_mul_f32_e32 v45, v52, v45
	v_mul_f32_e32 v46, v52, v46
	v_mul_f32_e32 v47, v52, v47
	v_lshlrev_b64 v[48:49], 11, v[82:83]
	v_lshl_add_u64 v[48:49], v[80:81], 0, v[48:49]
	v_mul_f32_e32 v41, v52, v41
	v_mul_f32_e32 v40, v52, v40
	v_mul_f32_e32 v42, v52, v42
	v_mul_f32_e32 v43, v52, v43
	v_mul_f32_e32 v37, v52, v37
	v_mul_f32_e32 v36, v52, v36
	v_mul_f32_e32 v38, v52, v38
	v_mul_f32_e32 v39, v52, v39
	v_mul_f32_e32 v33, v52, v33
	v_mul_f32_e32 v32, v52, v32
	v_mul_f32_e32 v34, v52, v34
	v_mul_f32_e32 v35, v52, v35
	s_waitcnt vmcnt(0)
; __device__ __forceinline__ unsigned cvt_pk_bf16(float lo, float hi) { unsigned r; asm volatile("v_cvt_pk_bf16_f32 %0, %1, %2" : "=v"(r) : "v"(lo), "v"(hi)); return r; }
; __device__ __forceinline__ float bflo(unsigned w) { return __uint_as_float(w << 16); }
; __device__ __forceinline__ float bfhi(unsigned w) { return __uint_as_float(w & 0xffff0000u); }
; __device__ __forceinline__ float fsigmoid(float x) { return __builtin_amdgcn_rcpf(1.0f + __expf(-x)); }
; __device__ __forceinline__ void attn_phase(LAS unsigned char* lds, const bf16_t* QKVZ, const float* sinks, bf16_t* OG, int G, int bid, int tid) {
;     ...
;             const bf16_t* zp = QKVZ + row * ATT_IN + 1536 + h * 64 + 4 * fq;
;             bf16_t* op = OG + row * D + h * 64 + 4 * fq;
; #pragma unroll
;             for (int dt = 0; dt < 4; ++dt) {
;                 const u32x2 zw = *(const u32x2*)(zp + dt * 16);
;                 const float z0 = bflo(zw.x), z1 = bfhi(zw.x), z2 = bflo(zw.y), z3 = bfhi(zw.y);
;                 const float r0 = o[dt][0] * inv * z0 * fsigmoid(z0), r1 = o[dt][1] * inv * z1 * fsigmoid(z1), r2 = o[dt][2] * inv * z2 * fsigmoid(z2), r3 = o[dt][3] * inv * z3 * fsigmoid(z3);
;                 u32x2 w; w.x = cvt_pk_bf16(r0, r1); w.y = cvt_pk_bf16(r2, r3);
;                 *(u32x2*)(op + dt * 16) = w;
;             }
	v_mov_b64_e32 v[54:55], v[200:201]
	v_lshlrev_b32_e32 v53, 16, v54
	v_mul_f32_e32 v44, v44, v53
	v_mul_f32_e32 v53, 0xbfb8aa3b, v53
	v_exp_f32_e32 v53, v53
	v_and_b32_e32 v54, 0xffff0000, v54
	v_lshlrev_b32_e32 v56, 16, v55
	v_mul_f32_e32 v45, v45, v54
	v_add_f32_e32 v53, 1.0, v53
	v_rcp_f32_e32 v53, v53
	v_and_b32_e32 v55, 0xffff0000, v55
	v_mul_f32_e32 v46, v46, v56
	v_mul_f32_e32 v47, v47, v55
	v_mul_f32_e32 v44, v44, v53
	v_mul_f32_e32 v53, 0xbfb8aa3b, v54
	v_exp_f32_e32 v53, v53
	s_nop 0
	v_add_f32_e32 v53, 1.0, v53
	v_rcp_f32_e32 v53, v53
	s_nop 0
	v_mul_f32_e32 v45, v45, v53
	v_mul_f32_e32 v53, 0xbfb8aa3b, v56
	v_exp_f32_e32 v53, v53
	v_cvt_pk_bf16_f32 v44, v44, v45
	s_nop 0
	v_add_f32_e32 v53, 1.0, v53
	v_rcp_f32_e32 v53, v53
	s_nop 0
	v_mul_f32_e32 v46, v46, v53
	v_mul_f32_e32 v53, 0xbfb8aa3b, v55
	v_exp_f32_e32 v53, v53
	s_nop 0
	v_add_f32_e32 v53, 1.0, v53
	v_rcp_f32_e32 v53, v53
	s_nop 0
	v_mul_f32_e32 v47, v47, v53
	v_cvt_pk_bf16_f32 v45, v46, v47
	global_store_dwordx2 v[48:49], v[44:45], off
	s_nop 1
	v_mov_b64_e32 v[44:45], v[202:203]
	v_lshlrev_b32_e32 v46, 16, v44
	v_and_b32_e32 v44, 0xffff0000, v44
	v_mul_f32_e32 v41, v41, v44
	v_mul_f32_e32 v44, 0xbfb8aa3b, v44
	v_exp_f32_e32 v44, v44
	v_lshlrev_b32_e32 v47, 16, v45
	v_and_b32_e32 v45, 0xffff0000, v45
	v_mul_f32_e32 v40, v40, v46
	v_add_f32_e32 v44, 1.0, v44
	v_rcp_f32_e32 v44, v44
	v_mul_f32_e32 v46, 0xbfb8aa3b, v46
	v_mul_f32_e32 v42, v42, v47
	v_exp_f32_e32 v46, v46
	v_mul_f32_e32 v41, v41, v44
	v_mul_f32_e32 v44, 0xbfb8aa3b, v47
	v_exp_f32_e32 v44, v44
	v_add_f32_e32 v46, 1.0, v46
	v_rcp_f32_e32 v46, v46
	v_mul_f32_e32 v43, v43, v45
	v_add_f32_e32 v44, 1.0, v44
	v_rcp_f32_e32 v44, v44
	v_mul_f32_e32 v40, v40, v46
	v_cvt_pk_bf16_f32 v40, v40, v41
	v_mul_f32_e32 v42, v42, v44
	v_mul_f32_e32 v44, 0xbfb8aa3b, v45
	v_exp_f32_e32 v44, v44
	s_nop 0
	v_add_f32_e32 v44, 1.0, v44
	v_rcp_f32_e32 v44, v44
	s_nop 0
	v_mul_f32_e32 v43, v43, v44
	v_cvt_pk_bf16_f32 v41, v42, v43
	global_store_dwordx2 v[48:49], v[40:41], off offset:32
	s_nop 1
	v_mov_b64_e32 v[40:41], v[204:205]
	v_lshlrev_b32_e32 v42, 16, v40
	v_and_b32_e32 v40, 0xffff0000, v40
	v_mul_f32_e32 v37, v37, v40
	v_mul_f32_e32 v40, 0xbfb8aa3b, v40
	v_exp_f32_e32 v40, v40
	v_lshlrev_b32_e32 v43, 16, v41
	v_and_b32_e32 v41, 0xffff0000, v41
	v_mul_f32_e32 v36, v36, v42
	v_add_f32_e32 v40, 1.0, v40
	v_rcp_f32_e32 v40, v40
	v_mul_f32_e32 v42, 0xbfb8aa3b, v42
	v_mul_f32_e32 v38, v38, v43
	v_exp_f32_e32 v42, v42
	v_mul_f32_e32 v37, v37, v40
	v_mul_f32_e32 v40, 0xbfb8aa3b, v43
	v_exp_f32_e32 v40, v40
	v_add_f32_e32 v42, 1.0, v42
	v_rcp_f32_e32 v42, v42
	v_mul_f32_e32 v39, v39, v41
	v_add_f32_e32 v40, 1.0, v40
	v_rcp_f32_e32 v40, v40
	v_mul_f32_e32 v36, v36, v42
	v_cvt_pk_bf16_f32 v36, v36, v37
	v_mul_f32_e32 v38, v38, v40
	v_mul_f32_e32 v40, 0xbfb8aa3b, v41
	v_exp_f32_e32 v40, v40
	s_nop 0
	v_add_f32_e32 v40, 1.0, v40
	v_rcp_f32_e32 v40, v40
	s_nop 0
	v_mul_f32_e32 v39, v39, v40
	v_cvt_pk_bf16_f32 v37, v38, v39
	global_store_dwordx2 v[48:49], v[36:37], off offset:64
	s_nop 1
	v_mov_b64_e32 v[36:37], v[206:207]
	v_lshlrev_b32_e32 v38, 16, v36
	v_and_b32_e32 v36, 0xffff0000, v36
	v_mul_f32_e32 v33, v33, v36
	v_mul_f32_e32 v36, 0xbfb8aa3b, v36
	v_exp_f32_e32 v36, v36
	v_lshlrev_b32_e32 v39, 16, v37
	v_and_b32_e32 v37, 0xffff0000, v37
	v_mul_f32_e32 v32, v32, v38
	v_add_f32_e32 v36, 1.0, v36
	v_rcp_f32_e32 v36, v36
	v_mul_f32_e32 v38, 0xbfb8aa3b, v38
	v_mul_f32_e32 v34, v34, v39
	v_exp_f32_e32 v38, v38
	v_mul_f32_e32 v33, v33, v36
	v_mul_f32_e32 v36, 0xbfb8aa3b, v39
	v_exp_f32_e32 v36, v36
	v_add_f32_e32 v38, 1.0, v38
	v_rcp_f32_e32 v38, v38
	v_mul_f32_e32 v35, v35, v37
	v_add_f32_e32 v36, 1.0, v36
	v_rcp_f32_e32 v36, v36
	v_mul_f32_e32 v32, v32, v38
	v_cvt_pk_bf16_f32 v32, v32, v33
	v_mul_f32_e32 v34, v34, v36
	v_mul_f32_e32 v36, 0xbfb8aa3b, v37
	v_exp_f32_e32 v36, v36
	s_nop 0
	v_add_f32_e32 v36, 1.0, v36
	v_rcp_f32_e32 v36, v36
	s_nop 0
	v_mul_f32_e32 v35, v35, v36
	v_cvt_pk_bf16_f32 v33, v34, v35
	global_store_dwordx2 v[48:49], v[32:33], off offset:96
	s_cbranch_scc0 .LBB0_246
	s_add_i32 s16, s16, s21
	s_and_b64 vcc, exec, s[10:11]
	s_mov_b32 s12, s24
	s_cbranch_vccz .LBB0_235
